# Woa GEMM: residual tile rows warmed into L2/MALL by 16 one-dword loads per wave at the start of the tile's K loop
# baseline (speedup 1.0000x reference)
.LBB0_639:
	s_ashr_i32 s49, s48, 31
	s_lshl_b64 s[54:55], s[48:49], 20
	s_add_u32 s54, s2, s54
	s_addc_u32 s55, s3, s55
	s_and_b64 s[56:57], s[8:9], exec
	s_cselect_b32 s49, s55, s63
	s_cselect_b32 s59, s54, s62
	s_ashr_i32 s47, s46, 31
	s_lshl_b64 s[56:57], s[46:47], 20
	s_add_u32 s56, s18, s56
	s_addc_u32 s57, s19, s57
	s_and_b64 s[66:67], s[8:9], exec
	s_cselect_b32 s47, s57, s65
	s_cselect_b32 s75, s56, s64
	s_add_u32 s76, s64, 0x100
	v_mov_b32_e32 v0, 0
	s_addc_u32 s77, s65, 0
	s_mov_b32 s78, -2
	s_waitcnt lgkmcnt(0)
	v_mov_b32_e32 v1, v0
	v_mov_b32_e32 v2, v0
	v_mov_b32_e32 v3, v0
	v_mov_b32_e32 v4, v0
	v_mov_b32_e32 v5, v0
	v_mov_b32_e32 v6, v0
	v_mov_b32_e32 v7, v0
	v_mov_b32_e32 v16, v0
	v_mov_b32_e32 v17, v0
	v_mov_b32_e32 v18, v0
	v_mov_b32_e32 v19, v0
	v_mov_b32_e32 v20, v0
	v_mov_b32_e32 v21, v0
	v_mov_b32_e32 v22, v0
	v_mov_b32_e32 v23, v0
	v_mov_b32_e32 v32, v0
	v_mov_b32_e32 v33, v0
	v_mov_b32_e32 v34, v0
	v_mov_b32_e32 v35, v0
	v_mov_b32_e32 v36, v0
	v_mov_b32_e32 v37, v0
	v_mov_b32_e32 v38, v0
	v_mov_b32_e32 v39, v0
	v_mov_b32_e32 v48, v0
	v_mov_b32_e32 v49, v0
	v_mov_b32_e32 v50, v0
	v_mov_b32_e32 v51, v0
	v_mov_b32_e32 v52, v0
	v_mov_b32_e32 v53, v0
	v_mov_b32_e32 v54, v0
	v_mov_b32_e32 v55, v0
	v_mov_b32_e32 v8, v0
	v_mov_b32_e32 v9, v0
	v_mov_b32_e32 v10, v0
	v_mov_b32_e32 v11, v0
	v_mov_b32_e32 v12, v0
	v_mov_b32_e32 v13, v0
	v_mov_b32_e32 v14, v0
	v_mov_b32_e32 v15, v0
	v_mov_b32_e32 v24, v0
	v_mov_b32_e32 v25, v0
	v_mov_b32_e32 v26, v0
	v_mov_b32_e32 v27, v0
	v_mov_b32_e32 v28, v0
	v_mov_b32_e32 v29, v0
	v_mov_b32_e32 v30, v0
	v_mov_b32_e32 v31, v0
	v_mov_b32_e32 v40, v0
	v_mov_b32_e32 v41, v0
	v_mov_b32_e32 v42, v0
	v_mov_b32_e32 v43, v0
	v_mov_b32_e32 v44, v0
	v_mov_b32_e32 v45, v0
	v_mov_b32_e32 v46, v0
	v_mov_b32_e32 v47, v0
	v_mov_b32_e32 v56, v0
	v_mov_b32_e32 v57, v0
	v_mov_b32_e32 v58, v0
	v_mov_b32_e32 v59, v0
	v_mov_b32_e32 v60, v0
	v_mov_b32_e32 v61, v0
	v_mov_b32_e32 v62, v0
	v_mov_b32_e32 v63, v0
	v_mov_b32_e32 v64, v0
	v_mov_b32_e32 v65, v0
	v_mov_b32_e32 v66, v0
	v_mov_b32_e32 v67, v0
	v_mov_b32_e32 v68, v0
	v_mov_b32_e32 v69, v0
	v_mov_b32_e32 v70, v0
	v_mov_b32_e32 v71, v0
	v_mov_b32_e32 v80, v0
	v_mov_b32_e32 v81, v0
	v_mov_b32_e32 v82, v0
	v_mov_b32_e32 v83, v0
	v_mov_b32_e32 v84, v0
	v_mov_b32_e32 v85, v0
	v_mov_b32_e32 v86, v0
	v_mov_b32_e32 v87, v0
	v_mov_b32_e32 v96, v0
	v_mov_b32_e32 v97, v0
	v_mov_b32_e32 v98, v0
	v_mov_b32_e32 v99, v0
	v_mov_b32_e32 v100, v0
	v_mov_b32_e32 v101, v0
	v_mov_b32_e32 v102, v0
	v_mov_b32_e32 v103, v0
	v_mov_b32_e32 v112, v0
	v_mov_b32_e32 v113, v0
	v_mov_b32_e32 v114, v0
	v_mov_b32_e32 v115, v0
	v_mov_b32_e32 v116, v0
	v_mov_b32_e32 v117, v0
	v_mov_b32_e32 v118, v0
	v_mov_b32_e32 v119, v0
	v_mov_b32_e32 v72, v0
	v_mov_b32_e32 v73, v0
	v_mov_b32_e32 v74, v0
	v_mov_b32_e32 v75, v0
	v_mov_b32_e32 v76, v0
	v_mov_b32_e32 v77, v0
	v_mov_b32_e32 v78, v0
	v_mov_b32_e32 v79, v0
	v_mov_b32_e32 v88, v0
	v_mov_b32_e32 v89, v0
	v_mov_b32_e32 v90, v0
	v_mov_b32_e32 v91, v0
	v_mov_b32_e32 v92, v0
	v_mov_b32_e32 v93, v0
	v_mov_b32_e32 v94, v0
	v_mov_b32_e32 v95, v0
	v_mov_b32_e32 v104, v0
	v_mov_b32_e32 v105, v0
	v_mov_b32_e32 v106, v0
	v_mov_b32_e32 v107, v0
	v_mov_b32_e32 v108, v0
	v_mov_b32_e32 v109, v0
	v_mov_b32_e32 v110, v0
	v_mov_b32_e32 v111, v0
	v_mov_b32_e32 v120, v0
	v_mov_b32_e32 v121, v0
	v_mov_b32_e32 v122, v0
	v_mov_b32_e32 v123, v0
	v_mov_b32_e32 v124, v0
	v_mov_b32_e32 v125, v0
	v_mov_b32_e32 v126, v0
	v_mov_b32_e32 v127, v0
	v_lshl_or_b32 v233, s58, 8, v151
	v_lshl_or_b32 v232, s60, 8, v152
	v_lshlrev_b32_e32 v233, 13, v233
	v_lshl_add_u32 v233, v232, 2, v233
	s_mov_b32 s94, s52
	s_mov_b32 s95, s53
	global_load_dword v232, v233, s[94:95]
	global_load_dword v232, v233, s[94:95] offset:512
	s_add_u32 s94, s94, 0x20000
	s_addc_u32 s95, s95, 0
	global_load_dword v232, v233, s[94:95]
	global_load_dword v232, v233, s[94:95] offset:512
	s_add_u32 s94, s94, 0x20000
	s_addc_u32 s95, s95, 0
	global_load_dword v232, v233, s[94:95]
	global_load_dword v232, v233, s[94:95] offset:512
	s_add_u32 s94, s94, 0x20000
	s_addc_u32 s95, s95, 0
	global_load_dword v232, v233, s[94:95]
	global_load_dword v232, v233, s[94:95] offset:512
	s_add_u32 s94, s94, 0xa0000
	s_addc_u32 s95, s95, 0
	global_load_dword v232, v233, s[94:95]
	global_load_dword v232, v233, s[94:95] offset:512
	s_add_u32 s94, s94, 0x20000
	s_addc_u32 s95, s95, 0
	global_load_dword v232, v233, s[94:95]
	global_load_dword v232, v233, s[94:95] offset:512
	s_add_u32 s94, s94, 0x20000
	s_addc_u32 s95, s95, 0
	global_load_dword v232, v233, s[94:95]
	global_load_dword v232, v233, s[94:95] offset:512
	s_add_u32 s94, s94, 0x20000
	s_addc_u32 s95, s95, 0
	global_load_dword v232, v233, s[94:95]
	global_load_dword v232, v233, s[94:95] offset:512
